# grid barrier: device-scope L1 invalidate (buffer_inv sc1) issued by every workgroup when it arrives (nothing is loaded through its CU L1 while it is parked) instead of after the release; leader issues
# speedup vs baseline: 1.0034x; 1.0034x over previous
.LBB0_824:
	s_or_b64 exec, exec, s[26:27]
	v_cvt_f32_u32_e32 v4, v2
	s_waitcnt vmcnt(0)
	v_readfirstlane_b32 s6, v3
	v_sub_u32_e32 v3, 0, v2
	v_rcp_iflag_f32_e32 v4, v4
	v_add_u32_e32 v5, s6, v1
	v_mul_f32_e32 v4, 0x4f7ffffe, v4
	v_cvt_u32_f32_e32 v4, v4
	v_mul_lo_u32 v1, v3, v4
	v_mul_hi_u32 v1, v4, v1
	v_add_u32_e32 v1, v4, v1
	v_mul_hi_u32 v1, v5, v1
	v_mul_lo_u32 v3, v1, v2
	v_sub_u32_e32 v3, v5, v3
	v_add_u32_e32 v4, 1, v1
	v_cmp_ge_u32_e32 vcc, v3, v2
	s_nop 1
	v_cndmask_b32_e32 v1, v1, v4, vcc
	v_sub_u32_e32 v4, v3, v2
	v_cndmask_b32_e32 v3, v3, v4, vcc
	v_add_u32_e32 v4, 1, v1
	v_cmp_ge_u32_e32 vcc, v3, v2
	v_add_u32_e32 v3, 1, v5
	s_nop 0
	v_cndmask_b32_e32 v1, v1, v4, vcc
	v_mul_lo_u32 v4, v2, v1
	v_add_u32_e32 v2, v4, v2
	v_cmp_ne_u32_e32 vcc, v3, v2
	s_and_saveexec_b64 s[10:11], vcc
	s_xor_b64 s[26:27], exec, s[10:11]
	s_cbranch_execz .LBB0_838
	v_readlane_b32 s10, v253, 39
	v_readlane_b32 s11, v253, 40
	s_waitcnt lgkmcnt(0)
	s_nop 3
	buffer_inv sc1
	global_load_dword v0, v141, s[10:11] sc1
	s_waitcnt vmcnt(0)
	v_cmp_eq_u32_e32 vcc, v0, v1
	s_and_saveexec_b64 s[28:29], vcc
	s_cbranch_execz .LBB0_837
	s_mov_b32 s6, 1
	s_mov_b64 s[30:31], 0
	s_branch .LBB0_828

.LBB0_837:
	s_or_b64 exec, exec, s[28:29]
	s_waitcnt vmcnt(0)
	s_waitcnt vmcnt(0)
.LBB0_838:
	s_andn2_saveexec_b64 s[10:11], s[26:27]
	s_cbranch_execz .LBB0_858
	s_mov_b64 s[26:27], exec
	buffer_wbl2 sc1
	buffer_inv sc1
	s_waitcnt lgkmcnt(0)
	s_waitcnt vmcnt(0)
	v_mbcnt_lo_u32_b32 v1, s26, 0
	v_mbcnt_hi_u32_b32 v1, s27, v1
	v_cmp_eq_u32_e32 vcc, 0, v1
	s_and_saveexec_b64 s[28:29], vcc
	s_cbranch_execz .LBB0_841
	s_bcnt1_i32_b64 s6, s[26:27]
	v_readlane_b32 s10, v253, 41
	v_mov_b32_e32 v2, s6
	v_readlane_b32 s11, v253, 42
	s_nop 4
	global_atomic_add v2, v141, v2, s[10:11] sc0

.LBB0_855:
	s_or_b64 exec, exec, s[26:27]
	s_mov_b64 s[26:27], exec
	v_mbcnt_lo_u32_b32 v0, s26, 0
	v_mbcnt_hi_u32_b32 v0, s27, v0
	v_cmp_eq_u32_e32 vcc, 0, v0
	s_waitcnt vmcnt(0)
	s_and_saveexec_b64 s[28:29], vcc
	s_cbranch_execz .LBB0_857
	s_bcnt1_i32_b64 s6, s[26:27]
	v_readlane_b32 s10, v253, 39
	v_mov_b32_e32 v0, s6
	v_readlane_b32 s11, v253, 40
	s_nop 4
	global_atomic_add v141, v0, s[10:11]
